# branch-GEMM mid hooks: gate loads software-pipelined over 3 rotating register buffers
# speedup vs baseline: 1.0080x; 1.0080x over previous
; __device__ __forceinline__ float frcp(float x) { return __builtin_amdgcn_rcpf(x); }
;     static __device__ __forceinline__ void unpack8(u32x4 w, f32x4& a, f32x4& b) { a = (f32x4){::bflo(w.x), ::bfhi(w.x), ::bflo(w.y), ::bfhi(w.y)}; b = (f32x4){::bflo(w.z), ::bfhi(w.z), ::bflo(w.w), ::bfhi(w.w)}; }
;     __device__ __forceinline__ void mid(f32x4 (&acc)[2][2][4][2], const Unit& u, int seg, int wr, int wc, int fr, int fq) const {
;     ...
;         const bf16_t* const Gn = G + (seg - 1) * 1024;
; #pragma unroll
;         for (int ai = 0; ai < 2; ++ai)
; #pragma unroll
;             for (int m = 0; m < 4; ++m) {
;                 const size_t r = (size_t)(row0 + ai * HALF + m * 16);
;                 u32x4 gn[2], gd[2];
; #pragma unroll
;                 for (int bj = 0; bj < 2; ++bj) { gn[bj] = *(const u32x4*)(Gn + r * 3072 + col0 + bj * HALF); gd[bj] = *(const u32x4*)(Gn + r * 3072 + 1024 + col0 + bj * HALF); }
;                 f32x4 rt[2][2];
;                 __builtin_amdgcn_sched_barrier(0);
; #pragma unroll
;                 for (int bj = 0; bj < 2; ++bj) {
;                     f32x4 a0, a1, d0, d1; unpack8(gn[bj], a0, a1); unpack8(gd[bj], d0, d1);
; #pragma unroll
;                     for (int j = 0; j < 4; ++j) { rt[bj][0][j] = fmaxf(a0[j], 1e-30f) * ::frcp(fmaxf(d0[j], 1e-30f)); rt[bj][1][j] = fmaxf(a1[j], 1e-30f) * ::frcp(fmaxf(d1[j], 1e-30f)); }
;                 }
;                 __builtin_amdgcn_sched_barrier(0);
; #pragma unroll
;                 for (int bj = 0; bj < 2; ++bj) { acc[ai][bj][m][0] = acc[ai][bj][m][0] * rt[bj][0]; acc[ai][bj][m][1] = acc[ai][bj][m][1] * rt[bj][1]; }
;             }
.LBB0_139:
	s_lshl_b32 s30, s14, 7
	s_nop 0
	v_lshl_add_u64 v[248:249], v[162:163], 0, s[58:59]
	v_add_co_u32_e32 v250, vcc, 0x127ff000, v248
	s_nop 1
	v_addc_co_u32_e32 v251, vcc, 0, v249, vcc
	v_add_co_u32_e32 v248, vcc, 0x12800000, v248
	s_nop 1
	v_addc_co_u32_e32 v249, vcc, 0, v249, vcc
	global_load_dwordx4 v[188:191], v[250:251], off offset:2048
	global_load_dwordx4 v[192:195], v[250:251], off offset:2304
	global_load_dwordx4 v[196:199], v[248:249], off
	global_load_dwordx4 v[200:203], v[248:249], off offset:256
	v_lshl_add_u64 v[248:249], v[160:161], 0, s[58:59]
	v_add_co_u32_e32 v250, vcc, s5, v248
	s_nop 1
	v_addc_co_u32_e32 v251, vcc, 0, v249, vcc
	v_add_co_u32_e32 v248, vcc, s6, v248
	s_nop 1
	v_addc_co_u32_e32 v249, vcc, 0, v249, vcc
	global_load_dwordx4 v[216:219], v[250:251], off offset:2048
	global_load_dwordx4 v[220:223], v[248:249], off
	global_load_dwordx4 v[224:227], v[250:251], off offset:2304
	global_load_dwordx4 v[228:231], v[248:249], off offset:256
	v_lshl_add_u64 v[248:249], v[158:159], 0, s[58:59]
	v_add_co_u32_e32 v250, vcc, s5, v248
	s_nop 1
	v_addc_co_u32_e32 v251, vcc, 0, v249, vcc
	v_add_co_u32_e32 v248, vcc, s6, v248
	s_nop 1
	v_addc_co_u32_e32 v249, vcc, 0, v249, vcc
	global_load_dwordx4 v[232:235], v[250:251], off offset:2048
	global_load_dwordx4 v[236:239], v[248:249], off
	global_load_dwordx4 v[240:243], v[250:251], off offset:2304
	global_load_dwordx4 v[244:247], v[248:249], off offset:256
	s_waitcnt vmcnt(8)
	v_lshlrev_b32_e32 v3, 16, v189
	v_lshlrev_b32_e32 v204, 16, v197
	v_max_f32_e32 v3, v3, v3
	v_lshlrev_b32_e32 v172, 16, v196
	v_and_b32_e32 v173, 0xffff0000, v196
	v_max_f32_e32 v196, 0xda24260, v3
	v_max_f32_e32 v3, v204, v204
	v_lshlrev_b32_e32 v184, 16, v191
	v_max_f32_e32 v3, 0xda24260, v3
	v_and_b32_e32 v140, 0xffff0000, v189
	v_and_b32_e32 v185, 0xffff0000, v191
	v_and_b32_e32 v205, 0xffff0000, v197
	v_lshlrev_b32_e32 v189, 16, v198
	v_and_b32_e32 v191, 0xffff0000, v198
	v_lshlrev_b32_e32 v197, 16, v199
	v_rcp_f32_e32 v198, v3
	v_max_f32_e32 v3, v184, v184
	v_lshlrev_b32_e32 v141, 16, v190
	v_max_f32_e32 v204, 0xda24260, v3
	v_max_f32_e32 v3, v197, v197
	v_max_f32_e32 v141, v141, v141
	v_max_f32_e32 v3, 0xda24260, v3
	v_lshlrev_b32_e32 v0, 16, v188
	v_and_b32_e32 v1, 0xffff0000, v188
	v_max_f32_e32 v188, 0xda24260, v141
	v_max_f32_e32 v141, v189, v189
	v_rcp_f32_e32 v206, v3
	v_max_f32_e32 v3, v140, v140
	v_max_f32_e32 v141, 0xda24260, v141
	v_max_f32_e32 v197, 0xda24260, v3
	v_max_f32_e32 v3, v205, v205
	v_and_b32_e32 v145, 0xffff0000, v190
	v_rcp_f32_e32 v190, v141
	v_max_f32_e32 v141, v173, v173
	v_max_f32_e32 v3, 0xda24260, v3
	v_and_b32_e32 v207, 0xffff0000, v199
	v_max_f32_e32 v141, 0xda24260, v141
	v_rcp_f32_e32 v199, v3
	v_max_f32_e32 v3, v185, v185
	v_rcp_f32_e32 v173, v141
	v_max_f32_e32 v141, v145, v145
	v_max_f32_e32 v205, 0xda24260, v3
	v_max_f32_e32 v3, v207, v207
	v_max_f32_e32 v189, 0xda24260, v141
	v_max_f32_e32 v141, v191, v191
	v_max_f32_e32 v3, 0xda24260, v3
	v_max_f32_e32 v141, 0xda24260, v141
	v_rcp_f32_e32 v207, v3
	v_lshlrev_b32_e32 v3, 16, v192
	v_rcp_f32_e32 v191, v141
	v_lshlrev_b32_e32 v141, 16, v193
	v_and_b32_e32 v145, 0xffff0000, v193
	v_lshlrev_b32_e32 v193, 16, v200
	v_max_f32_e32 v3, v3, v3
	v_and_b32_e32 v140, 0xffff0000, v192
	v_max_f32_e32 v192, 0xda24260, v3
	v_max_f32_e32 v3, v193, v193
	v_lshlrev_b32_e32 v184, 16, v194
	v_max_f32_e32 v3, 0xda24260, v3
	v_and_b32_e32 v185, 0xffff0000, v194
	v_lshlrev_b32_e32 v210, 16, v201
	v_and_b32_e32 v211, 0xffff0000, v201
	v_lshlrev_b32_e32 v201, 16, v202
	v_rcp_f32_e32 v194, v3
	v_max_f32_e32 v3, v184, v184
	v_lshlrev_b32_e32 v209, 16, v195
	v_and_b32_e32 v213, 0xffff0000, v195
	v_and_b32_e32 v195, 0xffff0000, v200
	v_max_f32_e32 v200, 0xda24260, v3
	v_max_f32_e32 v3, v201, v201
	v_max_f32_e32 v3, 0xda24260, v3
	v_and_b32_e32 v208, 0xffff0000, v202
	v_rcp_f32_e32 v202, v3
	v_max_f32_e32 v3, v140, v140
	v_max_f32_e32 v193, 0xda24260, v3
	v_max_f32_e32 v3, v195, v195
	v_max_f32_e32 v3, 0xda24260, v3
	v_rcp_f32_e32 v195, v3
	v_max_f32_e32 v3, v185, v185
	v_max_f32_e32 v201, 0xda24260, v3
	v_max_f32_e32 v3, v208, v208
	v_max_f32_e32 v3, 0xda24260, v3
	v_lshlrev_b32_e32 v214, 16, v203
	v_and_b32_e32 v215, 0xffff0000, v203
	v_rcp_f32_e32 v203, v3
	v_max_f32_e32 v3, v141, v141
	v_max_f32_e32 v208, 0xda24260, v3
	v_max_f32_e32 v3, v210, v210
	v_max_f32_e32 v3, 0xda24260, v3
	v_rcp_f32_e32 v210, v3
	v_max_f32_e32 v3, v209, v209
	v_max_f32_e32 v212, 0xda24260, v3
	v_max_f32_e32 v3, v214, v214
	v_max_f32_e32 v140, v211, v211
	v_max_f32_e32 v3, 0xda24260, v3
	v_max_f32_e32 v140, 0xda24260, v140
	v_max_f32_e32 v172, v172, v172
	v_rcp_f32_e32 v214, v3
	v_max_f32_e32 v3, v145, v145
	v_rcp_f32_e32 v211, v140
	v_max_f32_e32 v140, v215, v215
	v_max_f32_e32 v0, v0, v0
	v_max_f32_e32 v172, 0xda24260, v172
	v_max_f32_e32 v1, v1, v1
	v_max_f32_e32 v140, 0xda24260, v140
	v_max_f32_e32 v209, 0xda24260, v3
	v_max_f32_e32 v3, v213, v213
	v_max_f32_e32 v0, 0xda24260, v0
	v_rcp_f32_e32 v172, v172
	v_max_f32_e32 v1, 0xda24260, v1
	v_rcp_f32_e32 v215, v140
	v_max_f32_e32 v213, 0xda24260, v3
	v_pk_mul_f32 v[0:1], v[0:1], v[172:173]
	v_pk_mul_f32 v[172:173], v[196:197], v[198:199]
	v_pk_mul_f32 v[128:129], v[128:129], v[0:1]
	v_pk_mul_f32 v[0:1], v[188:189], v[190:191]
	v_pk_mul_f32 v[130:131], v[130:131], v[172:173]
	v_pk_mul_f32 v[172:173], v[204:205], v[206:207]
	v_pk_mul_f32 v[124:125], v[124:125], v[0:1]
	v_pk_mul_f32 v[0:1], v[192:193], v[194:195]
	v_pk_mul_f32 v[126:127], v[126:127], v[172:173]
	v_pk_mul_f32 v[172:173], v[208:209], v[210:211]
	v_pk_mul_f32 v[120:121], v[120:121], v[0:1]
	v_pk_mul_f32 v[0:1], v[200:201], v[202:203]
	v_pk_mul_f32 v[122:123], v[122:123], v[172:173]
	v_pk_mul_f32 v[172:173], v[212:213], v[214:215]
	v_pk_mul_f32 v[116:117], v[116:117], v[0:1]
	v_pk_mul_f32 v[118:119], v[118:119], v[172:173]
	v_lshl_add_u64 v[248:249], v[156:157], 0, s[58:59]
	v_add_co_u32_e32 v250, vcc, s5, v248
	s_nop 1
	v_addc_co_u32_e32 v251, vcc, 0, v249, vcc
	v_add_co_u32_e32 v248, vcc, s6, v248
	s_nop 1
	v_addc_co_u32_e32 v249, vcc, 0, v249, vcc
	global_load_dwordx4 v[188:191], v[250:251], off offset:2048
	global_load_dwordx4 v[192:195], v[248:249], off
	global_load_dwordx4 v[196:199], v[250:251], off offset:2304
	global_load_dwordx4 v[200:203], v[248:249], off offset:256
	s_waitcnt vmcnt(8)
; __device__ __forceinline__ float frcp(float x) { return __builtin_amdgcn_rcpf(x); }
;     static __device__ __forceinline__ void unpack8(u32x4 w, f32x4& a, f32x4& b) { a = (f32x4){::bflo(w.x), ::bfhi(w.x), ::bflo(w.y), ::bfhi(w.y)}; b = (f32x4){::bflo(w.z), ::bfhi(w.z), ::bflo(w.w), ::bfhi(w.w)}; }
;     __device__ __forceinline__ void mid(f32x4 (&acc)[2][2][4][2], const Unit& u, int seg, int wr, int wc, int fr, int fq) const {
;     ...
;         const bf16_t* const Gn = G + (seg - 1) * 1024;
; #pragma unroll
;         for (int ai = 0; ai < 2; ++ai)
; #pragma unroll
;             for (int m = 0; m < 4; ++m) {
;                 const size_t r = (size_t)(row0 + ai * HALF + m * 16);
;                 u32x4 gn[2], gd[2];
; #pragma unroll
;                 for (int bj = 0; bj < 2; ++bj) { gn[bj] = *(const u32x4*)(Gn + r * 3072 + col0 + bj * HALF); gd[bj] = *(const u32x4*)(Gn + r * 3072 + 1024 + col0 + bj * HALF); }
;                 f32x4 rt[2][2];
;                 __builtin_amdgcn_sched_barrier(0);
; #pragma unroll
;                 for (int bj = 0; bj < 2; ++bj) {
;                     f32x4 a0, a1, d0, d1; unpack8(gn[bj], a0, a1); unpack8(gd[bj], d0, d1);
; #pragma unroll
;                     for (int j = 0; j < 4; ++j) { rt[bj][0][j] = fmaxf(a0[j], 1e-30f) * ::frcp(fmaxf(d0[j], 1e-30f)); rt[bj][1][j] = fmaxf(a1[j], 1e-30f) * ::frcp(fmaxf(d1[j], 1e-30f)); }
;                 }
;                 __builtin_amdgcn_sched_barrier(0);
; #pragma unroll
;                 for (int bj = 0; bj < 2; ++bj) { acc[ai][bj][m][0] = acc[ai][bj][m][0] * rt[bj][0]; acc[ai][bj][m][1] = acc[ai][bj][m][1] * rt[bj][1]; }
;             }
	v_lshlrev_b32_e32 v3, 16, v217
	v_lshlrev_b32_e32 v204, 16, v221
	v_max_f32_e32 v3, v3, v3
	v_lshlrev_b32_e32 v172, 16, v220
	v_and_b32_e32 v173, 0xffff0000, v220
	v_max_f32_e32 v220, 0xda24260, v3
	v_max_f32_e32 v3, v204, v204
	v_lshlrev_b32_e32 v184, 16, v219
	v_max_f32_e32 v3, 0xda24260, v3
	v_and_b32_e32 v140, 0xffff0000, v217
	v_and_b32_e32 v185, 0xffff0000, v219
	v_and_b32_e32 v205, 0xffff0000, v221
	v_lshlrev_b32_e32 v217, 16, v222
	v_and_b32_e32 v219, 0xffff0000, v222
	v_lshlrev_b32_e32 v221, 16, v223
	v_rcp_f32_e32 v222, v3
	v_max_f32_e32 v3, v184, v184
	v_lshlrev_b32_e32 v141, 16, v218
	v_max_f32_e32 v204, 0xda24260, v3
	v_max_f32_e32 v3, v221, v221
	v_max_f32_e32 v141, v141, v141
	v_max_f32_e32 v3, 0xda24260, v3
	v_lshlrev_b32_e32 v0, 16, v216
	v_and_b32_e32 v1, 0xffff0000, v216
	v_max_f32_e32 v216, 0xda24260, v141
	v_max_f32_e32 v141, v217, v217
	v_rcp_f32_e32 v206, v3
	v_max_f32_e32 v3, v140, v140
	v_max_f32_e32 v141, 0xda24260, v141
	v_max_f32_e32 v221, 0xda24260, v3
	v_max_f32_e32 v3, v205, v205
	v_and_b32_e32 v145, 0xffff0000, v218
	v_rcp_f32_e32 v218, v141
	v_max_f32_e32 v141, v173, v173
	v_max_f32_e32 v3, 0xda24260, v3
	v_and_b32_e32 v207, 0xffff0000, v223
	v_max_f32_e32 v141, 0xda24260, v141
	v_rcp_f32_e32 v223, v3
	v_max_f32_e32 v3, v185, v185
	v_rcp_f32_e32 v173, v141
	v_max_f32_e32 v141, v145, v145
	v_max_f32_e32 v205, 0xda24260, v3
	v_max_f32_e32 v3, v207, v207
	v_max_f32_e32 v217, 0xda24260, v141
	v_max_f32_e32 v141, v219, v219
	v_max_f32_e32 v3, 0xda24260, v3
	v_max_f32_e32 v141, 0xda24260, v141
	v_rcp_f32_e32 v207, v3
	v_lshlrev_b32_e32 v3, 16, v224
	v_rcp_f32_e32 v219, v141
	v_lshlrev_b32_e32 v141, 16, v225
	v_and_b32_e32 v145, 0xffff0000, v225
	v_lshlrev_b32_e32 v225, 16, v228
	v_max_f32_e32 v3, v3, v3
	v_and_b32_e32 v140, 0xffff0000, v224
	v_max_f32_e32 v224, 0xda24260, v3
	v_max_f32_e32 v3, v225, v225
	v_lshlrev_b32_e32 v184, 16, v226
	v_max_f32_e32 v3, 0xda24260, v3
	v_and_b32_e32 v185, 0xffff0000, v226
	v_lshlrev_b32_e32 v210, 16, v229
	v_and_b32_e32 v211, 0xffff0000, v229
	v_lshlrev_b32_e32 v229, 16, v230
	v_rcp_f32_e32 v226, v3
	v_max_f32_e32 v3, v184, v184
	v_lshlrev_b32_e32 v209, 16, v227
	v_and_b32_e32 v213, 0xffff0000, v227
	v_and_b32_e32 v227, 0xffff0000, v228
	v_max_f32_e32 v228, 0xda24260, v3
	v_max_f32_e32 v3, v229, v229
	v_max_f32_e32 v3, 0xda24260, v3
	v_and_b32_e32 v208, 0xffff0000, v230
	v_rcp_f32_e32 v230, v3
	v_max_f32_e32 v3, v140, v140
	v_max_f32_e32 v225, 0xda24260, v3
	v_max_f32_e32 v3, v227, v227
	v_max_f32_e32 v3, 0xda24260, v3
	v_rcp_f32_e32 v227, v3
	v_max_f32_e32 v3, v185, v185
	v_max_f32_e32 v229, 0xda24260, v3
	v_max_f32_e32 v3, v208, v208
	v_max_f32_e32 v3, 0xda24260, v3
	v_lshlrev_b32_e32 v214, 16, v231
	v_and_b32_e32 v215, 0xffff0000, v231
	v_rcp_f32_e32 v231, v3
	v_max_f32_e32 v3, v141, v141
	v_max_f32_e32 v208, 0xda24260, v3
	v_max_f32_e32 v3, v210, v210
	v_max_f32_e32 v3, 0xda24260, v3
	v_rcp_f32_e32 v210, v3
	v_max_f32_e32 v3, v209, v209
	v_max_f32_e32 v212, 0xda24260, v3
	v_max_f32_e32 v3, v214, v214
	v_max_f32_e32 v140, v211, v211
	v_max_f32_e32 v3, 0xda24260, v3
	v_max_f32_e32 v140, 0xda24260, v140
	v_max_f32_e32 v172, v172, v172
	v_rcp_f32_e32 v214, v3
	v_max_f32_e32 v3, v145, v145
	v_rcp_f32_e32 v211, v140
	v_max_f32_e32 v140, v215, v215
	v_max_f32_e32 v0, v0, v0
	v_max_f32_e32 v172, 0xda24260, v172
	v_max_f32_e32 v1, v1, v1
	v_max_f32_e32 v140, 0xda24260, v140
	v_max_f32_e32 v209, 0xda24260, v3
	v_max_f32_e32 v3, v213, v213
	v_max_f32_e32 v0, 0xda24260, v0
	v_rcp_f32_e32 v172, v172
	v_max_f32_e32 v1, 0xda24260, v1
	v_rcp_f32_e32 v215, v140
	v_max_f32_e32 v213, 0xda24260, v3
	v_pk_mul_f32 v[0:1], v[0:1], v[172:173]
	v_pk_mul_f32 v[172:173], v[220:221], v[222:223]
	v_pk_mul_f32 v[112:113], v[112:113], v[0:1]
	v_pk_mul_f32 v[0:1], v[216:217], v[218:219]
	v_pk_mul_f32 v[114:115], v[114:115], v[172:173]
	v_pk_mul_f32 v[172:173], v[204:205], v[206:207]
	v_pk_mul_f32 v[108:109], v[108:109], v[0:1]
	v_pk_mul_f32 v[0:1], v[224:225], v[226:227]
	v_pk_mul_f32 v[110:111], v[110:111], v[172:173]
	v_pk_mul_f32 v[172:173], v[208:209], v[210:211]
	v_pk_mul_f32 v[104:105], v[104:105], v[0:1]
	v_pk_mul_f32 v[0:1], v[228:229], v[230:231]
	v_pk_mul_f32 v[106:107], v[106:107], v[172:173]
	v_pk_mul_f32 v[172:173], v[212:213], v[214:215]
	v_pk_mul_f32 v[100:101], v[100:101], v[0:1]
	v_pk_mul_f32 v[102:103], v[102:103], v[172:173]
	v_lshl_add_u64 v[248:249], v[154:155], 0, s[58:59]
	v_add_co_u32_e32 v250, vcc, s5, v248
	s_nop 1
	v_addc_co_u32_e32 v251, vcc, 0, v249, vcc
	v_add_co_u32_e32 v248, vcc, s6, v248
	s_nop 1
	v_addc_co_u32_e32 v249, vcc, 0, v249, vcc
	global_load_dwordx4 v[216:219], v[250:251], off offset:2048
	global_load_dwordx4 v[220:223], v[248:249], off
	global_load_dwordx4 v[224:227], v[250:251], off offset:2304
	global_load_dwordx4 v[228:231], v[248:249], off offset:256
	s_waitcnt vmcnt(8)
; __device__ __forceinline__ float frcp(float x) { return __builtin_amdgcn_rcpf(x); }
;     static __device__ __forceinline__ void unpack8(u32x4 w, f32x4& a, f32x4& b) { a = (f32x4){::bflo(w.x), ::bfhi(w.x), ::bflo(w.y), ::bfhi(w.y)}; b = (f32x4){::bflo(w.z), ::bfhi(w.z), ::bflo(w.w), ::bfhi(w.w)}; }
;     __device__ __forceinline__ void mid(f32x4 (&acc)[2][2][4][2], const Unit& u, int seg, int wr, int wc, int fr, int fq) const {
;     ...
;         const bf16_t* const Gn = G + (seg - 1) * 1024;
; #pragma unroll
;         for (int ai = 0; ai < 2; ++ai)
; #pragma unroll
;             for (int m = 0; m < 4; ++m) {
;                 const size_t r = (size_t)(row0 + ai * HALF + m * 16);
;                 u32x4 gn[2], gd[2];
; #pragma unroll
;                 for (int bj = 0; bj < 2; ++bj) { gn[bj] = *(const u32x4*)(Gn + r * 3072 + col0 + bj * HALF); gd[bj] = *(const u32x4*)(Gn + r * 3072 + 1024 + col0 + bj * HALF); }
;                 f32x4 rt[2][2];
;                 __builtin_amdgcn_sched_barrier(0);
; #pragma unroll
;                 for (int bj = 0; bj < 2; ++bj) {
;                     f32x4 a0, a1, d0, d1; unpack8(gn[bj], a0, a1); unpack8(gd[bj], d0, d1);
; #pragma unroll
;                     for (int j = 0; j < 4; ++j) { rt[bj][0][j] = fmaxf(a0[j], 1e-30f) * ::frcp(fmaxf(d0[j], 1e-30f)); rt[bj][1][j] = fmaxf(a1[j], 1e-30f) * ::frcp(fmaxf(d1[j], 1e-30f)); }
;                 }
;                 __builtin_amdgcn_sched_barrier(0);
; #pragma unroll
;                 for (int bj = 0; bj < 2; ++bj) { acc[ai][bj][m][0] = acc[ai][bj][m][0] * rt[bj][0]; acc[ai][bj][m][1] = acc[ai][bj][m][1] * rt[bj][1]; }
;             }
	v_lshlrev_b32_e32 v3, 16, v233
	v_lshlrev_b32_e32 v204, 16, v237
	v_max_f32_e32 v3, v3, v3
	v_lshlrev_b32_e32 v172, 16, v236
	v_and_b32_e32 v173, 0xffff0000, v236
	v_max_f32_e32 v236, 0xda24260, v3
	v_max_f32_e32 v3, v204, v204
	v_lshlrev_b32_e32 v184, 16, v235
	v_max_f32_e32 v3, 0xda24260, v3
	v_and_b32_e32 v140, 0xffff0000, v233
	v_and_b32_e32 v185, 0xffff0000, v235
	v_and_b32_e32 v205, 0xffff0000, v237
	v_lshlrev_b32_e32 v233, 16, v238
	v_and_b32_e32 v235, 0xffff0000, v238
	v_lshlrev_b32_e32 v237, 16, v239
	v_rcp_f32_e32 v238, v3
	v_max_f32_e32 v3, v184, v184
	v_lshlrev_b32_e32 v141, 16, v234
	v_max_f32_e32 v204, 0xda24260, v3
	v_max_f32_e32 v3, v237, v237
	v_max_f32_e32 v141, v141, v141
	v_max_f32_e32 v3, 0xda24260, v3
	v_lshlrev_b32_e32 v0, 16, v232
	v_and_b32_e32 v1, 0xffff0000, v232
	v_max_f32_e32 v232, 0xda24260, v141
	v_max_f32_e32 v141, v233, v233
	v_rcp_f32_e32 v206, v3
	v_max_f32_e32 v3, v140, v140
	v_max_f32_e32 v141, 0xda24260, v141
	v_max_f32_e32 v237, 0xda24260, v3
	v_max_f32_e32 v3, v205, v205
	v_and_b32_e32 v145, 0xffff0000, v234
	v_rcp_f32_e32 v234, v141
	v_max_f32_e32 v141, v173, v173
	v_max_f32_e32 v3, 0xda24260, v3
	v_and_b32_e32 v207, 0xffff0000, v239
	v_max_f32_e32 v141, 0xda24260, v141
	v_rcp_f32_e32 v239, v3
	v_max_f32_e32 v3, v185, v185
	v_rcp_f32_e32 v173, v141
	v_max_f32_e32 v141, v145, v145
	v_max_f32_e32 v205, 0xda24260, v3
	v_max_f32_e32 v3, v207, v207
	v_max_f32_e32 v233, 0xda24260, v141
	v_max_f32_e32 v141, v235, v235
	v_max_f32_e32 v3, 0xda24260, v3
	v_max_f32_e32 v141, 0xda24260, v141
	v_rcp_f32_e32 v207, v3
	v_lshlrev_b32_e32 v3, 16, v240
	v_rcp_f32_e32 v235, v141
	v_lshlrev_b32_e32 v141, 16, v241
	v_and_b32_e32 v145, 0xffff0000, v241
	v_lshlrev_b32_e32 v241, 16, v244
	v_max_f32_e32 v3, v3, v3
	v_and_b32_e32 v140, 0xffff0000, v240
	v_max_f32_e32 v240, 0xda24260, v3
	v_max_f32_e32 v3, v241, v241
	v_lshlrev_b32_e32 v184, 16, v242
	v_max_f32_e32 v3, 0xda24260, v3
	v_and_b32_e32 v185, 0xffff0000, v242
	v_lshlrev_b32_e32 v210, 16, v245
	v_and_b32_e32 v211, 0xffff0000, v245
	v_lshlrev_b32_e32 v245, 16, v246
	v_rcp_f32_e32 v242, v3
	v_max_f32_e32 v3, v184, v184
	v_lshlrev_b32_e32 v209, 16, v243
	v_and_b32_e32 v213, 0xffff0000, v243
	v_and_b32_e32 v243, 0xffff0000, v244
	v_max_f32_e32 v244, 0xda24260, v3
	v_max_f32_e32 v3, v245, v245
	v_max_f32_e32 v3, 0xda24260, v3
	v_and_b32_e32 v208, 0xffff0000, v246
	v_rcp_f32_e32 v246, v3
	v_max_f32_e32 v3, v140, v140
	v_max_f32_e32 v241, 0xda24260, v3
	v_max_f32_e32 v3, v243, v243
	v_max_f32_e32 v3, 0xda24260, v3
	v_rcp_f32_e32 v243, v3
	v_max_f32_e32 v3, v185, v185
	v_max_f32_e32 v245, 0xda24260, v3
	v_max_f32_e32 v3, v208, v208
	v_max_f32_e32 v3, 0xda24260, v3
	v_lshlrev_b32_e32 v214, 16, v247
	v_and_b32_e32 v215, 0xffff0000, v247
	v_rcp_f32_e32 v247, v3
	v_max_f32_e32 v3, v141, v141
	v_max_f32_e32 v208, 0xda24260, v3
	v_max_f32_e32 v3, v210, v210
	v_max_f32_e32 v3, 0xda24260, v3
	v_rcp_f32_e32 v210, v3
	v_max_f32_e32 v3, v209, v209
	v_max_f32_e32 v212, 0xda24260, v3
	v_max_f32_e32 v3, v214, v214
	v_max_f32_e32 v140, v211, v211
	v_max_f32_e32 v3, 0xda24260, v3
	v_max_f32_e32 v140, 0xda24260, v140
	v_max_f32_e32 v172, v172, v172
	v_rcp_f32_e32 v214, v3
	v_max_f32_e32 v3, v145, v145
	v_rcp_f32_e32 v211, v140
	v_max_f32_e32 v140, v215, v215
	v_max_f32_e32 v0, v0, v0
	v_max_f32_e32 v172, 0xda24260, v172
	v_max_f32_e32 v1, v1, v1
	v_max_f32_e32 v140, 0xda24260, v140
	v_max_f32_e32 v209, 0xda24260, v3
	v_max_f32_e32 v3, v213, v213
	v_max_f32_e32 v0, 0xda24260, v0
	v_rcp_f32_e32 v172, v172
	v_max_f32_e32 v1, 0xda24260, v1
	v_rcp_f32_e32 v215, v140
	v_max_f32_e32 v213, 0xda24260, v3
	v_pk_mul_f32 v[0:1], v[0:1], v[172:173]
	v_pk_mul_f32 v[172:173], v[236:237], v[238:239]
	v_pk_mul_f32 v[96:97], v[96:97], v[0:1]
	v_pk_mul_f32 v[0:1], v[232:233], v[234:235]
	v_pk_mul_f32 v[98:99], v[98:99], v[172:173]
	v_pk_mul_f32 v[172:173], v[204:205], v[206:207]
	v_pk_mul_f32 v[92:93], v[92:93], v[0:1]
	v_pk_mul_f32 v[0:1], v[240:241], v[242:243]
	v_pk_mul_f32 v[94:95], v[94:95], v[172:173]
	v_pk_mul_f32 v[172:173], v[208:209], v[210:211]
	v_pk_mul_f32 v[88:89], v[88:89], v[0:1]
	v_pk_mul_f32 v[0:1], v[244:245], v[246:247]
	v_pk_mul_f32 v[90:91], v[90:91], v[172:173]
	v_pk_mul_f32 v[172:173], v[212:213], v[214:215]
	v_pk_mul_f32 v[84:85], v[84:85], v[0:1]
	v_pk_mul_f32 v[86:87], v[86:87], v[172:173]
	v_lshl_add_u64 v[248:249], v[152:153], 0, s[58:59]
	v_add_co_u32_e32 v250, vcc, s5, v248
	s_nop 1
	v_addc_co_u32_e32 v251, vcc, 0, v249, vcc
	v_add_co_u32_e32 v248, vcc, s6, v248
	s_nop 1
	v_addc_co_u32_e32 v249, vcc, 0, v249, vcc
	global_load_dwordx4 v[232:235], v[250:251], off offset:2048
	global_load_dwordx4 v[236:239], v[248:249], off
	global_load_dwordx4 v[240:243], v[250:251], off offset:2304
	global_load_dwordx4 v[244:247], v[248:249], off offset:256
	s_waitcnt vmcnt(8)
; __device__ __forceinline__ float frcp(float x) { return __builtin_amdgcn_rcpf(x); }
;     static __device__ __forceinline__ void unpack8(u32x4 w, f32x4& a, f32x4& b) { a = (f32x4){::bflo(w.x), ::bfhi(w.x), ::bflo(w.y), ::bfhi(w.y)}; b = (f32x4){::bflo(w.z), ::bfhi(w.z), ::bflo(w.w), ::bfhi(w.w)}; }
;     __device__ __forceinline__ void mid(f32x4 (&acc)[2][2][4][2], const Unit& u, int seg, int wr, int wc, int fr, int fq) const {
;     ...
;         const bf16_t* const Gn = G + (seg - 1) * 1024;
; #pragma unroll
;         for (int ai = 0; ai < 2; ++ai)
; #pragma unroll
;             for (int m = 0; m < 4; ++m) {
;                 const size_t r = (size_t)(row0 + ai * HALF + m * 16);
;                 u32x4 gn[2], gd[2];
; #pragma unroll
;                 for (int bj = 0; bj < 2; ++bj) { gn[bj] = *(const u32x4*)(Gn + r * 3072 + col0 + bj * HALF); gd[bj] = *(const u32x4*)(Gn + r * 3072 + 1024 + col0 + bj * HALF); }
;                 f32x4 rt[2][2];
;                 __builtin_amdgcn_sched_barrier(0);
; #pragma unroll
;                 for (int bj = 0; bj < 2; ++bj) {
;                     f32x4 a0, a1, d0, d1; unpack8(gn[bj], a0, a1); unpack8(gd[bj], d0, d1);
; #pragma unroll
;                     for (int j = 0; j < 4; ++j) { rt[bj][0][j] = fmaxf(a0[j], 1e-30f) * ::frcp(fmaxf(d0[j], 1e-30f)); rt[bj][1][j] = fmaxf(a1[j], 1e-30f) * ::frcp(fmaxf(d1[j], 1e-30f)); }
;                 }
;                 __builtin_amdgcn_sched_barrier(0);
; #pragma unroll
;                 for (int bj = 0; bj < 2; ++bj) { acc[ai][bj][m][0] = acc[ai][bj][m][0] * rt[bj][0]; acc[ai][bj][m][1] = acc[ai][bj][m][1] * rt[bj][1]; }
;             }
	v_lshlrev_b32_e32 v3, 16, v189
	v_lshlrev_b32_e32 v204, 16, v193
	v_max_f32_e32 v3, v3, v3
	v_lshlrev_b32_e32 v172, 16, v192
	v_and_b32_e32 v173, 0xffff0000, v192
	v_max_f32_e32 v192, 0xda24260, v3
	v_max_f32_e32 v3, v204, v204
	v_lshlrev_b32_e32 v184, 16, v191
	v_max_f32_e32 v3, 0xda24260, v3
	v_and_b32_e32 v140, 0xffff0000, v189
	v_and_b32_e32 v185, 0xffff0000, v191
	v_and_b32_e32 v205, 0xffff0000, v193
	v_lshlrev_b32_e32 v189, 16, v194
	v_and_b32_e32 v191, 0xffff0000, v194
	v_lshlrev_b32_e32 v193, 16, v195
	v_rcp_f32_e32 v194, v3
	v_max_f32_e32 v3, v184, v184
	v_lshlrev_b32_e32 v141, 16, v190
	v_max_f32_e32 v204, 0xda24260, v3
	v_max_f32_e32 v3, v193, v193
	v_max_f32_e32 v141, v141, v141
	v_max_f32_e32 v3, 0xda24260, v3
	v_lshlrev_b32_e32 v0, 16, v188
	v_and_b32_e32 v1, 0xffff0000, v188
	v_max_f32_e32 v188, 0xda24260, v141
	v_max_f32_e32 v141, v189, v189
	v_rcp_f32_e32 v206, v3
	v_max_f32_e32 v3, v140, v140
	v_max_f32_e32 v141, 0xda24260, v141
	v_max_f32_e32 v193, 0xda24260, v3
	v_max_f32_e32 v3, v205, v205
	v_and_b32_e32 v145, 0xffff0000, v190
	v_rcp_f32_e32 v190, v141
	v_max_f32_e32 v141, v173, v173
	v_max_f32_e32 v3, 0xda24260, v3
	v_and_b32_e32 v207, 0xffff0000, v195
	v_max_f32_e32 v141, 0xda24260, v141
	v_rcp_f32_e32 v195, v3
	v_max_f32_e32 v3, v185, v185
	v_rcp_f32_e32 v173, v141
	v_max_f32_e32 v141, v145, v145
	v_max_f32_e32 v205, 0xda24260, v3
	v_max_f32_e32 v3, v207, v207
	v_max_f32_e32 v189, 0xda24260, v141
	v_max_f32_e32 v141, v191, v191
	v_max_f32_e32 v3, 0xda24260, v3
	v_max_f32_e32 v141, 0xda24260, v141
	v_rcp_f32_e32 v207, v3
	v_lshlrev_b32_e32 v3, 16, v196
	v_rcp_f32_e32 v191, v141
	v_lshlrev_b32_e32 v141, 16, v197
	v_and_b32_e32 v145, 0xffff0000, v197
	v_lshlrev_b32_e32 v197, 16, v200
	v_max_f32_e32 v3, v3, v3
	v_and_b32_e32 v140, 0xffff0000, v196
	v_max_f32_e32 v196, 0xda24260, v3
	v_max_f32_e32 v3, v197, v197
	v_lshlrev_b32_e32 v184, 16, v198
	v_max_f32_e32 v3, 0xda24260, v3
	v_and_b32_e32 v185, 0xffff0000, v198
	v_lshlrev_b32_e32 v210, 16, v201
	v_and_b32_e32 v211, 0xffff0000, v201
	v_lshlrev_b32_e32 v201, 16, v202
	v_rcp_f32_e32 v198, v3
	v_max_f32_e32 v3, v184, v184
	v_lshlrev_b32_e32 v209, 16, v199
	v_and_b32_e32 v213, 0xffff0000, v199
	v_and_b32_e32 v199, 0xffff0000, v200
	v_max_f32_e32 v200, 0xda24260, v3
	v_max_f32_e32 v3, v201, v201
	v_max_f32_e32 v3, 0xda24260, v3
	v_and_b32_e32 v208, 0xffff0000, v202
	v_rcp_f32_e32 v202, v3
	v_max_f32_e32 v3, v140, v140
	v_max_f32_e32 v197, 0xda24260, v3
	v_max_f32_e32 v3, v199, v199
	v_max_f32_e32 v3, 0xda24260, v3
	v_rcp_f32_e32 v199, v3
	v_max_f32_e32 v3, v185, v185
	v_max_f32_e32 v201, 0xda24260, v3
	v_max_f32_e32 v3, v208, v208
	v_max_f32_e32 v3, 0xda24260, v3
	v_lshlrev_b32_e32 v214, 16, v203
	v_and_b32_e32 v215, 0xffff0000, v203
	v_rcp_f32_e32 v203, v3
	v_max_f32_e32 v3, v141, v141
	v_max_f32_e32 v208, 0xda24260, v3
	v_max_f32_e32 v3, v210, v210
	v_max_f32_e32 v3, 0xda24260, v3
	v_rcp_f32_e32 v210, v3
	v_max_f32_e32 v3, v209, v209
	v_max_f32_e32 v212, 0xda24260, v3
	v_max_f32_e32 v3, v214, v214
	v_max_f32_e32 v140, v211, v211
	v_max_f32_e32 v3, 0xda24260, v3
	v_max_f32_e32 v140, 0xda24260, v140
	v_max_f32_e32 v172, v172, v172
	v_rcp_f32_e32 v214, v3
	v_max_f32_e32 v3, v145, v145
	v_rcp_f32_e32 v211, v140
	v_max_f32_e32 v140, v215, v215
	v_max_f32_e32 v0, v0, v0
	v_max_f32_e32 v172, 0xda24260, v172
	v_max_f32_e32 v1, v1, v1
	v_max_f32_e32 v140, 0xda24260, v140
	v_max_f32_e32 v209, 0xda24260, v3
	v_max_f32_e32 v3, v213, v213
	v_max_f32_e32 v0, 0xda24260, v0
	v_rcp_f32_e32 v172, v172
	v_max_f32_e32 v1, 0xda24260, v1
	v_rcp_f32_e32 v215, v140
	v_max_f32_e32 v213, 0xda24260, v3
	v_pk_mul_f32 v[0:1], v[0:1], v[172:173]
	v_pk_mul_f32 v[172:173], v[192:193], v[194:195]
	v_pk_mul_f32 v[80:81], v[80:81], v[0:1]
	v_pk_mul_f32 v[0:1], v[188:189], v[190:191]
	v_pk_mul_f32 v[82:83], v[82:83], v[172:173]
	v_pk_mul_f32 v[172:173], v[204:205], v[206:207]
	v_pk_mul_f32 v[76:77], v[76:77], v[0:1]
	v_pk_mul_f32 v[0:1], v[196:197], v[198:199]
	v_pk_mul_f32 v[78:79], v[78:79], v[172:173]
	v_pk_mul_f32 v[172:173], v[208:209], v[210:211]
	v_pk_mul_f32 v[72:73], v[72:73], v[0:1]
	v_pk_mul_f32 v[0:1], v[200:201], v[202:203]
	v_pk_mul_f32 v[74:75], v[74:75], v[172:173]
	v_pk_mul_f32 v[172:173], v[212:213], v[214:215]
	v_pk_mul_f32 v[68:69], v[68:69], v[0:1]
	v_pk_mul_f32 v[70:71], v[70:71], v[172:173]
	v_lshl_add_u64 v[248:249], v[150:151], 0, s[58:59]
	v_add_co_u32_e32 v250, vcc, s5, v248
	s_nop 1
	v_addc_co_u32_e32 v251, vcc, 0, v249, vcc
	v_add_co_u32_e32 v248, vcc, s6, v248
	s_nop 1
	v_addc_co_u32_e32 v249, vcc, 0, v249, vcc
	global_load_dwordx4 v[188:191], v[250:251], off offset:2048
	global_load_dwordx4 v[192:195], v[248:249], off
	global_load_dwordx4 v[196:199], v[250:251], off offset:2304
	global_load_dwordx4 v[200:203], v[248:249], off offset:256
	s_waitcnt vmcnt(8)
; __device__ __forceinline__ float frcp(float x) { return __builtin_amdgcn_rcpf(x); }
;     static __device__ __forceinline__ void unpack8(u32x4 w, f32x4& a, f32x4& b) { a = (f32x4){::bflo(w.x), ::bfhi(w.x), ::bflo(w.y), ::bfhi(w.y)}; b = (f32x4){::bflo(w.z), ::bfhi(w.z), ::bflo(w.w), ::bfhi(w.w)}; }
;     __device__ __forceinline__ void mid(f32x4 (&acc)[2][2][4][2], const Unit& u, int seg, int wr, int wc, int fr, int fq) const {
;     ...
;         const bf16_t* const Gn = G + (seg - 1) * 1024;
; #pragma unroll
;         for (int ai = 0; ai < 2; ++ai)
; #pragma unroll
;             for (int m = 0; m < 4; ++m) {
;                 const size_t r = (size_t)(row0 + ai * HALF + m * 16);
;                 u32x4 gn[2], gd[2];
; #pragma unroll
;                 for (int bj = 0; bj < 2; ++bj) { gn[bj] = *(const u32x4*)(Gn + r * 3072 + col0 + bj * HALF); gd[bj] = *(const u32x4*)(Gn + r * 3072 + 1024 + col0 + bj * HALF); }
;                 f32x4 rt[2][2];
;                 __builtin_amdgcn_sched_barrier(0);
; #pragma unroll
;                 for (int bj = 0; bj < 2; ++bj) {
;                     f32x4 a0, a1, d0, d1; unpack8(gn[bj], a0, a1); unpack8(gd[bj], d0, d1);
; #pragma unroll
;                     for (int j = 0; j < 4; ++j) { rt[bj][0][j] = fmaxf(a0[j], 1e-30f) * ::frcp(fmaxf(d0[j], 1e-30f)); rt[bj][1][j] = fmaxf(a1[j], 1e-30f) * ::frcp(fmaxf(d1[j], 1e-30f)); }
;                 }
;                 __builtin_amdgcn_sched_barrier(0);
; #pragma unroll
;                 for (int bj = 0; bj < 2; ++bj) { acc[ai][bj][m][0] = acc[ai][bj][m][0] * rt[bj][0]; acc[ai][bj][m][1] = acc[ai][bj][m][1] * rt[bj][1]; }
;             }
	v_lshlrev_b32_e32 v3, 16, v217
	v_lshlrev_b32_e32 v204, 16, v221
	v_max_f32_e32 v3, v3, v3
	v_lshlrev_b32_e32 v172, 16, v220
	v_and_b32_e32 v173, 0xffff0000, v220
	v_max_f32_e32 v220, 0xda24260, v3
	v_max_f32_e32 v3, v204, v204
	v_lshlrev_b32_e32 v184, 16, v219
	v_max_f32_e32 v3, 0xda24260, v3
	v_and_b32_e32 v140, 0xffff0000, v217
	v_and_b32_e32 v185, 0xffff0000, v219
	v_and_b32_e32 v205, 0xffff0000, v221
	v_lshlrev_b32_e32 v217, 16, v222
	v_and_b32_e32 v219, 0xffff0000, v222
	v_lshlrev_b32_e32 v221, 16, v223
	v_rcp_f32_e32 v222, v3
	v_max_f32_e32 v3, v184, v184
	v_lshlrev_b32_e32 v141, 16, v218
	v_max_f32_e32 v204, 0xda24260, v3
	v_max_f32_e32 v3, v221, v221
	v_max_f32_e32 v141, v141, v141
	v_max_f32_e32 v3, 0xda24260, v3
	v_lshlrev_b32_e32 v0, 16, v216
	v_and_b32_e32 v1, 0xffff0000, v216
	v_max_f32_e32 v216, 0xda24260, v141
	v_max_f32_e32 v141, v217, v217
	v_rcp_f32_e32 v206, v3
	v_max_f32_e32 v3, v140, v140
	v_max_f32_e32 v141, 0xda24260, v141
	v_max_f32_e32 v221, 0xda24260, v3
	v_max_f32_e32 v3, v205, v205
	v_and_b32_e32 v145, 0xffff0000, v218
	v_rcp_f32_e32 v218, v141
	v_max_f32_e32 v141, v173, v173
	v_max_f32_e32 v3, 0xda24260, v3
	v_and_b32_e32 v207, 0xffff0000, v223
	v_max_f32_e32 v141, 0xda24260, v141
	v_rcp_f32_e32 v223, v3
	v_max_f32_e32 v3, v185, v185
	v_rcp_f32_e32 v173, v141
	v_max_f32_e32 v141, v145, v145
	v_max_f32_e32 v205, 0xda24260, v3
	v_max_f32_e32 v3, v207, v207
	v_max_f32_e32 v217, 0xda24260, v141
	v_max_f32_e32 v141, v219, v219
	v_max_f32_e32 v3, 0xda24260, v3
	v_max_f32_e32 v141, 0xda24260, v141
	v_rcp_f32_e32 v207, v3
	v_lshlrev_b32_e32 v3, 16, v224
	v_rcp_f32_e32 v219, v141
	v_lshlrev_b32_e32 v141, 16, v225
	v_and_b32_e32 v145, 0xffff0000, v225
	v_lshlrev_b32_e32 v225, 16, v228
	v_max_f32_e32 v3, v3, v3
	v_and_b32_e32 v140, 0xffff0000, v224
	v_max_f32_e32 v224, 0xda24260, v3
	v_max_f32_e32 v3, v225, v225
	v_lshlrev_b32_e32 v184, 16, v226
	v_max_f32_e32 v3, 0xda24260, v3
	v_and_b32_e32 v185, 0xffff0000, v226
	v_lshlrev_b32_e32 v210, 16, v229
	v_and_b32_e32 v211, 0xffff0000, v229
	v_lshlrev_b32_e32 v229, 16, v230
	v_rcp_f32_e32 v226, v3
	v_max_f32_e32 v3, v184, v184
	v_lshlrev_b32_e32 v209, 16, v227
	v_and_b32_e32 v213, 0xffff0000, v227
	v_and_b32_e32 v227, 0xffff0000, v228
	v_max_f32_e32 v228, 0xda24260, v3
	v_max_f32_e32 v3, v229, v229
	v_max_f32_e32 v3, 0xda24260, v3
	v_and_b32_e32 v208, 0xffff0000, v230
	v_rcp_f32_e32 v230, v3
	v_max_f32_e32 v3, v140, v140
	v_max_f32_e32 v225, 0xda24260, v3
	v_max_f32_e32 v3, v227, v227
	v_max_f32_e32 v3, 0xda24260, v3
	v_rcp_f32_e32 v227, v3
	v_max_f32_e32 v3, v185, v185
	v_max_f32_e32 v229, 0xda24260, v3
	v_max_f32_e32 v3, v208, v208
	v_max_f32_e32 v3, 0xda24260, v3
	v_lshlrev_b32_e32 v214, 16, v231
	v_and_b32_e32 v215, 0xffff0000, v231
	v_rcp_f32_e32 v231, v3
	v_max_f32_e32 v3, v141, v141
	v_max_f32_e32 v208, 0xda24260, v3
	v_max_f32_e32 v3, v210, v210
	v_max_f32_e32 v3, 0xda24260, v3
	v_rcp_f32_e32 v210, v3
	v_max_f32_e32 v3, v209, v209
	v_max_f32_e32 v212, 0xda24260, v3
	v_max_f32_e32 v3, v214, v214
	v_max_f32_e32 v140, v211, v211
	v_max_f32_e32 v3, 0xda24260, v3
	v_max_f32_e32 v140, 0xda24260, v140
	v_max_f32_e32 v172, v172, v172
	v_rcp_f32_e32 v214, v3
	v_max_f32_e32 v3, v145, v145
	v_rcp_f32_e32 v211, v140
	v_max_f32_e32 v140, v215, v215
	v_max_f32_e32 v0, v0, v0
	v_max_f32_e32 v172, 0xda24260, v172
	v_max_f32_e32 v1, v1, v1
	v_max_f32_e32 v140, 0xda24260, v140
	v_max_f32_e32 v209, 0xda24260, v3
	v_max_f32_e32 v3, v213, v213
	v_max_f32_e32 v0, 0xda24260, v0
	v_rcp_f32_e32 v172, v172
	v_max_f32_e32 v1, 0xda24260, v1
	v_rcp_f32_e32 v215, v140
	v_max_f32_e32 v213, 0xda24260, v3
	v_pk_mul_f32 v[0:1], v[0:1], v[172:173]
	v_pk_mul_f32 v[172:173], v[220:221], v[222:223]
	v_pk_mul_f32 v[64:65], v[64:65], v[0:1]
	v_pk_mul_f32 v[0:1], v[216:217], v[218:219]
	v_pk_mul_f32 v[66:67], v[66:67], v[172:173]
	v_pk_mul_f32 v[172:173], v[204:205], v[206:207]
	v_pk_mul_f32 v[60:61], v[60:61], v[0:1]
	v_pk_mul_f32 v[0:1], v[224:225], v[226:227]
	v_pk_mul_f32 v[62:63], v[62:63], v[172:173]
	v_pk_mul_f32 v[172:173], v[208:209], v[210:211]
	v_pk_mul_f32 v[56:57], v[56:57], v[0:1]
	v_pk_mul_f32 v[0:1], v[228:229], v[230:231]
	v_pk_mul_f32 v[58:59], v[58:59], v[172:173]
	v_pk_mul_f32 v[172:173], v[212:213], v[214:215]
	v_pk_mul_f32 v[52:53], v[52:53], v[0:1]
	v_pk_mul_f32 v[54:55], v[54:55], v[172:173]
	v_lshl_add_u64 v[248:249], v[148:149], 0, s[58:59]
	v_add_co_u32_e32 v250, vcc, s5, v248
	s_nop 1
	v_addc_co_u32_e32 v251, vcc, 0, v249, vcc
	v_add_co_u32_e32 v248, vcc, s6, v248
	s_nop 1
	v_addc_co_u32_e32 v249, vcc, 0, v249, vcc
	global_load_dwordx4 v[216:219], v[250:251], off offset:2048
	global_load_dwordx4 v[220:223], v[248:249], off
	global_load_dwordx4 v[224:227], v[250:251], off offset:2304
	global_load_dwordx4 v[228:231], v[248:249], off offset:256
	s_waitcnt vmcnt(8)
; __device__ __forceinline__ float frcp(float x) { return __builtin_amdgcn_rcpf(x); }
;     static __device__ __forceinline__ void unpack8(u32x4 w, f32x4& a, f32x4& b) { a = (f32x4){::bflo(w.x), ::bfhi(w.x), ::bflo(w.y), ::bfhi(w.y)}; b = (f32x4){::bflo(w.z), ::bfhi(w.z), ::bflo(w.w), ::bfhi(w.w)}; }
;     __device__ __forceinline__ void mid(f32x4 (&acc)[2][2][4][2], const Unit& u, int seg, int wr, int wc, int fr, int fq) const {
;     ...
;         const bf16_t* const Gn = G + (seg - 1) * 1024;
; #pragma unroll
;         for (int ai = 0; ai < 2; ++ai)
; #pragma unroll
;             for (int m = 0; m < 4; ++m) {
;                 const size_t r = (size_t)(row0 + ai * HALF + m * 16);
;                 u32x4 gn[2], gd[2];
; #pragma unroll
;                 for (int bj = 0; bj < 2; ++bj) { gn[bj] = *(const u32x4*)(Gn + r * 3072 + col0 + bj * HALF); gd[bj] = *(const u32x4*)(Gn + r * 3072 + 1024 + col0 + bj * HALF); }
;                 f32x4 rt[2][2];
;                 __builtin_amdgcn_sched_barrier(0);
; #pragma unroll
;                 for (int bj = 0; bj < 2; ++bj) {
;                     f32x4 a0, a1, d0, d1; unpack8(gn[bj], a0, a1); unpack8(gd[bj], d0, d1);
; #pragma unroll
;                     for (int j = 0; j < 4; ++j) { rt[bj][0][j] = fmaxf(a0[j], 1e-30f) * ::frcp(fmaxf(d0[j], 1e-30f)); rt[bj][1][j] = fmaxf(a1[j], 1e-30f) * ::frcp(fmaxf(d1[j], 1e-30f)); }
;                 }
;                 __builtin_amdgcn_sched_barrier(0);
; #pragma unroll
;                 for (int bj = 0; bj < 2; ++bj) { acc[ai][bj][m][0] = acc[ai][bj][m][0] * rt[bj][0]; acc[ai][bj][m][1] = acc[ai][bj][m][1] * rt[bj][1]; }
;             }
	v_lshlrev_b32_e32 v3, 16, v233
	v_lshlrev_b32_e32 v204, 16, v237
	v_max_f32_e32 v3, v3, v3
	v_lshlrev_b32_e32 v172, 16, v236
	v_and_b32_e32 v173, 0xffff0000, v236
	v_max_f32_e32 v236, 0xda24260, v3
	v_max_f32_e32 v3, v204, v204
	v_lshlrev_b32_e32 v184, 16, v235
	v_max_f32_e32 v3, 0xda24260, v3
	v_and_b32_e32 v140, 0xffff0000, v233
	v_and_b32_e32 v185, 0xffff0000, v235
	v_and_b32_e32 v205, 0xffff0000, v237
	v_lshlrev_b32_e32 v233, 16, v238
	v_and_b32_e32 v235, 0xffff0000, v238
	v_lshlrev_b32_e32 v237, 16, v239
	v_rcp_f32_e32 v238, v3
	v_max_f32_e32 v3, v184, v184
	v_lshlrev_b32_e32 v141, 16, v234
	v_max_f32_e32 v204, 0xda24260, v3
	v_max_f32_e32 v3, v237, v237
	v_max_f32_e32 v141, v141, v141
	v_max_f32_e32 v3, 0xda24260, v3
	v_lshlrev_b32_e32 v0, 16, v232
	v_and_b32_e32 v1, 0xffff0000, v232
	v_max_f32_e32 v232, 0xda24260, v141
	v_max_f32_e32 v141, v233, v233
	v_rcp_f32_e32 v206, v3
	v_max_f32_e32 v3, v140, v140
	v_max_f32_e32 v141, 0xda24260, v141
	v_max_f32_e32 v237, 0xda24260, v3
	v_max_f32_e32 v3, v205, v205
	v_and_b32_e32 v145, 0xffff0000, v234
	v_rcp_f32_e32 v234, v141
	v_max_f32_e32 v141, v173, v173
	v_max_f32_e32 v3, 0xda24260, v3
	v_and_b32_e32 v207, 0xffff0000, v239
	v_max_f32_e32 v141, 0xda24260, v141
	v_rcp_f32_e32 v239, v3
	v_max_f32_e32 v3, v185, v185
	v_rcp_f32_e32 v173, v141
	v_max_f32_e32 v141, v145, v145
	v_max_f32_e32 v205, 0xda24260, v3
	v_max_f32_e32 v3, v207, v207
	v_max_f32_e32 v233, 0xda24260, v141
	v_max_f32_e32 v141, v235, v235
	v_max_f32_e32 v3, 0xda24260, v3
	v_max_f32_e32 v141, 0xda24260, v141
	v_rcp_f32_e32 v207, v3
	v_lshlrev_b32_e32 v3, 16, v240
	v_rcp_f32_e32 v235, v141
	v_lshlrev_b32_e32 v141, 16, v241
	v_and_b32_e32 v145, 0xffff0000, v241
	v_lshlrev_b32_e32 v241, 16, v244
	v_max_f32_e32 v3, v3, v3
	v_and_b32_e32 v140, 0xffff0000, v240
	v_max_f32_e32 v240, 0xda24260, v3
	v_max_f32_e32 v3, v241, v241
	v_lshlrev_b32_e32 v184, 16, v242
	v_max_f32_e32 v3, 0xda24260, v3
	v_and_b32_e32 v185, 0xffff0000, v242
	v_lshlrev_b32_e32 v210, 16, v245
	v_and_b32_e32 v211, 0xffff0000, v245
	v_lshlrev_b32_e32 v245, 16, v246
	v_rcp_f32_e32 v242, v3
	v_max_f32_e32 v3, v184, v184
	v_lshlrev_b32_e32 v209, 16, v243
	v_and_b32_e32 v213, 0xffff0000, v243
	v_and_b32_e32 v243, 0xffff0000, v244
	v_max_f32_e32 v244, 0xda24260, v3
	v_max_f32_e32 v3, v245, v245
	v_max_f32_e32 v3, 0xda24260, v3
	v_and_b32_e32 v208, 0xffff0000, v246
	v_rcp_f32_e32 v246, v3
	v_max_f32_e32 v3, v140, v140
	v_max_f32_e32 v241, 0xda24260, v3
	v_max_f32_e32 v3, v243, v243
	v_max_f32_e32 v3, 0xda24260, v3
	v_rcp_f32_e32 v243, v3
	v_max_f32_e32 v3, v185, v185
	v_max_f32_e32 v245, 0xda24260, v3
	v_max_f32_e32 v3, v208, v208
	v_max_f32_e32 v3, 0xda24260, v3
	v_lshlrev_b32_e32 v214, 16, v247
	v_and_b32_e32 v215, 0xffff0000, v247
	v_rcp_f32_e32 v247, v3
	v_max_f32_e32 v3, v141, v141
	v_max_f32_e32 v208, 0xda24260, v3
	v_max_f32_e32 v3, v210, v210
	v_max_f32_e32 v3, 0xda24260, v3
	v_rcp_f32_e32 v210, v3
	v_max_f32_e32 v3, v209, v209
	v_max_f32_e32 v212, 0xda24260, v3
	v_max_f32_e32 v3, v214, v214
	v_max_f32_e32 v140, v211, v211
	v_max_f32_e32 v3, 0xda24260, v3
	v_max_f32_e32 v140, 0xda24260, v140
	v_max_f32_e32 v172, v172, v172
	v_rcp_f32_e32 v214, v3
	v_max_f32_e32 v3, v145, v145
	v_rcp_f32_e32 v211, v140
	v_max_f32_e32 v140, v215, v215
	v_max_f32_e32 v0, v0, v0
	v_max_f32_e32 v172, 0xda24260, v172
	v_max_f32_e32 v1, v1, v1
	v_max_f32_e32 v140, 0xda24260, v140
	v_max_f32_e32 v209, 0xda24260, v3
	v_max_f32_e32 v3, v213, v213
	v_max_f32_e32 v0, 0xda24260, v0
	v_rcp_f32_e32 v172, v172
	v_max_f32_e32 v1, 0xda24260, v1
	v_rcp_f32_e32 v215, v140
	v_max_f32_e32 v213, 0xda24260, v3
	v_pk_mul_f32 v[0:1], v[0:1], v[172:173]
	v_pk_mul_f32 v[172:173], v[236:237], v[238:239]
	v_pk_mul_f32 v[48:49], v[48:49], v[0:1]
	v_pk_mul_f32 v[0:1], v[232:233], v[234:235]
	v_pk_mul_f32 v[50:51], v[50:51], v[172:173]
	v_pk_mul_f32 v[172:173], v[204:205], v[206:207]
	v_pk_mul_f32 v[44:45], v[44:45], v[0:1]
	v_pk_mul_f32 v[0:1], v[240:241], v[242:243]
	v_pk_mul_f32 v[46:47], v[46:47], v[172:173]
	v_pk_mul_f32 v[172:173], v[208:209], v[210:211]
	v_pk_mul_f32 v[40:41], v[40:41], v[0:1]
	v_pk_mul_f32 v[0:1], v[244:245], v[246:247]
	v_pk_mul_f32 v[42:43], v[42:43], v[172:173]
	v_pk_mul_f32 v[172:173], v[212:213], v[214:215]
	v_pk_mul_f32 v[36:37], v[36:37], v[0:1]
	v_pk_mul_f32 v[38:39], v[38:39], v[172:173]
	s_waitcnt vmcnt(4)
; __device__ __forceinline__ float frcp(float x) { return __builtin_amdgcn_rcpf(x); }
;     static __device__ __forceinline__ void unpack8(u32x4 w, f32x4& a, f32x4& b) { a = (f32x4){::bflo(w.x), ::bfhi(w.x), ::bflo(w.y), ::bfhi(w.y)}; b = (f32x4){::bflo(w.z), ::bfhi(w.z), ::bflo(w.w), ::bfhi(w.w)}; }
;     __device__ __forceinline__ void mid(f32x4 (&acc)[2][2][4][2], const Unit& u, int seg, int wr, int wc, int fr, int fq) const {
;     ...
;         const bf16_t* const Gn = G + (seg - 1) * 1024;
; #pragma unroll
;         for (int ai = 0; ai < 2; ++ai)
; #pragma unroll
;             for (int m = 0; m < 4; ++m) {
;                 const size_t r = (size_t)(row0 + ai * HALF + m * 16);
;                 u32x4 gn[2], gd[2];
; #pragma unroll
;                 for (int bj = 0; bj < 2; ++bj) { gn[bj] = *(const u32x4*)(Gn + r * 3072 + col0 + bj * HALF); gd[bj] = *(const u32x4*)(Gn + r * 3072 + 1024 + col0 + bj * HALF); }
;                 f32x4 rt[2][2];
;                 __builtin_amdgcn_sched_barrier(0);
; #pragma unroll
;                 for (int bj = 0; bj < 2; ++bj) {
;                     f32x4 a0, a1, d0, d1; unpack8(gn[bj], a0, a1); unpack8(gd[bj], d0, d1);
; #pragma unroll
;                     for (int j = 0; j < 4; ++j) { rt[bj][0][j] = fmaxf(a0[j], 1e-30f) * ::frcp(fmaxf(d0[j], 1e-30f)); rt[bj][1][j] = fmaxf(a1[j], 1e-30f) * ::frcp(fmaxf(d1[j], 1e-30f)); }
;                 }
;                 __builtin_amdgcn_sched_barrier(0);
; #pragma unroll
;                 for (int bj = 0; bj < 2; ++bj) { acc[ai][bj][m][0] = acc[ai][bj][m][0] * rt[bj][0]; acc[ai][bj][m][1] = acc[ai][bj][m][1] * rt[bj][1]; }
;             }
	v_lshlrev_b32_e32 v3, 16, v189
	v_lshlrev_b32_e32 v204, 16, v193
	v_max_f32_e32 v3, v3, v3
	v_lshlrev_b32_e32 v172, 16, v192
	v_and_b32_e32 v173, 0xffff0000, v192
	v_max_f32_e32 v192, 0xda24260, v3
	v_max_f32_e32 v3, v204, v204
	v_lshlrev_b32_e32 v184, 16, v191
	v_max_f32_e32 v3, 0xda24260, v3
	v_and_b32_e32 v140, 0xffff0000, v189
	v_and_b32_e32 v185, 0xffff0000, v191
	v_and_b32_e32 v205, 0xffff0000, v193
	v_lshlrev_b32_e32 v189, 16, v194
	v_and_b32_e32 v191, 0xffff0000, v194
	v_lshlrev_b32_e32 v193, 16, v195
	v_rcp_f32_e32 v194, v3
	v_max_f32_e32 v3, v184, v184
	v_lshlrev_b32_e32 v141, 16, v190
	v_max_f32_e32 v204, 0xda24260, v3
	v_max_f32_e32 v3, v193, v193
	v_max_f32_e32 v141, v141, v141
	v_max_f32_e32 v3, 0xda24260, v3
	v_lshlrev_b32_e32 v0, 16, v188
	v_and_b32_e32 v1, 0xffff0000, v188
	v_max_f32_e32 v188, 0xda24260, v141
	v_max_f32_e32 v141, v189, v189
	v_rcp_f32_e32 v206, v3
	v_max_f32_e32 v3, v140, v140
	v_max_f32_e32 v141, 0xda24260, v141
	v_max_f32_e32 v193, 0xda24260, v3
	v_max_f32_e32 v3, v205, v205
	v_and_b32_e32 v145, 0xffff0000, v190
	v_rcp_f32_e32 v190, v141
	v_max_f32_e32 v141, v173, v173
	v_max_f32_e32 v3, 0xda24260, v3
	v_and_b32_e32 v207, 0xffff0000, v195
	v_max_f32_e32 v141, 0xda24260, v141
	v_rcp_f32_e32 v195, v3
	v_max_f32_e32 v3, v185, v185
	v_rcp_f32_e32 v173, v141
	v_max_f32_e32 v141, v145, v145
	v_max_f32_e32 v205, 0xda24260, v3
	v_max_f32_e32 v3, v207, v207
	v_max_f32_e32 v189, 0xda24260, v141
	v_max_f32_e32 v141, v191, v191
	v_max_f32_e32 v3, 0xda24260, v3
	v_max_f32_e32 v141, 0xda24260, v141
	v_rcp_f32_e32 v207, v3
	v_lshlrev_b32_e32 v3, 16, v196
	v_rcp_f32_e32 v191, v141
	v_lshlrev_b32_e32 v141, 16, v197
	v_and_b32_e32 v145, 0xffff0000, v197
	v_lshlrev_b32_e32 v197, 16, v200
	v_max_f32_e32 v3, v3, v3
	v_and_b32_e32 v140, 0xffff0000, v196
	v_max_f32_e32 v196, 0xda24260, v3
	v_max_f32_e32 v3, v197, v197
	v_lshlrev_b32_e32 v184, 16, v198
	v_max_f32_e32 v3, 0xda24260, v3
	v_and_b32_e32 v185, 0xffff0000, v198
	v_lshlrev_b32_e32 v210, 16, v201
	v_and_b32_e32 v211, 0xffff0000, v201
	v_lshlrev_b32_e32 v201, 16, v202
	v_rcp_f32_e32 v198, v3
	v_max_f32_e32 v3, v184, v184
	v_lshlrev_b32_e32 v209, 16, v199
	v_and_b32_e32 v213, 0xffff0000, v199
	v_and_b32_e32 v199, 0xffff0000, v200
	v_max_f32_e32 v200, 0xda24260, v3
	v_max_f32_e32 v3, v201, v201
	v_max_f32_e32 v3, 0xda24260, v3
	v_and_b32_e32 v208, 0xffff0000, v202
	v_rcp_f32_e32 v202, v3
	v_max_f32_e32 v3, v140, v140
	v_max_f32_e32 v197, 0xda24260, v3
	v_max_f32_e32 v3, v199, v199
	v_max_f32_e32 v3, 0xda24260, v3
	v_rcp_f32_e32 v199, v3
	v_max_f32_e32 v3, v185, v185
	v_max_f32_e32 v201, 0xda24260, v3
	v_max_f32_e32 v3, v208, v208
	v_max_f32_e32 v3, 0xda24260, v3
	v_lshlrev_b32_e32 v214, 16, v203
	v_and_b32_e32 v215, 0xffff0000, v203
	v_rcp_f32_e32 v203, v3
	v_max_f32_e32 v3, v141, v141
	v_max_f32_e32 v208, 0xda24260, v3
	v_max_f32_e32 v3, v210, v210
	v_max_f32_e32 v3, 0xda24260, v3
	v_rcp_f32_e32 v210, v3
	v_max_f32_e32 v3, v209, v209
	v_max_f32_e32 v212, 0xda24260, v3
	v_max_f32_e32 v3, v214, v214
	v_max_f32_e32 v140, v211, v211
	v_max_f32_e32 v3, 0xda24260, v3
	v_max_f32_e32 v140, 0xda24260, v140
	v_max_f32_e32 v172, v172, v172
	v_rcp_f32_e32 v214, v3
	v_max_f32_e32 v3, v145, v145
	v_rcp_f32_e32 v211, v140
	v_max_f32_e32 v140, v215, v215
	v_max_f32_e32 v0, v0, v0
	v_max_f32_e32 v172, 0xda24260, v172
	v_max_f32_e32 v1, v1, v1
	v_max_f32_e32 v140, 0xda24260, v140
	v_max_f32_e32 v209, 0xda24260, v3
	v_max_f32_e32 v3, v213, v213
	v_max_f32_e32 v0, 0xda24260, v0
	v_rcp_f32_e32 v172, v172
	v_max_f32_e32 v1, 0xda24260, v1
	v_rcp_f32_e32 v215, v140
	v_max_f32_e32 v213, 0xda24260, v3
	v_pk_mul_f32 v[0:1], v[0:1], v[172:173]
	v_pk_mul_f32 v[172:173], v[192:193], v[194:195]
	v_pk_mul_f32 v[32:33], v[32:33], v[0:1]
	v_pk_mul_f32 v[0:1], v[188:189], v[190:191]
	v_pk_mul_f32 v[34:35], v[34:35], v[172:173]
	v_pk_mul_f32 v[172:173], v[204:205], v[206:207]
	v_pk_mul_f32 v[28:29], v[28:29], v[0:1]
	v_pk_mul_f32 v[0:1], v[196:197], v[198:199]
	v_pk_mul_f32 v[30:31], v[30:31], v[172:173]
	v_pk_mul_f32 v[172:173], v[208:209], v[210:211]
	v_pk_mul_f32 v[24:25], v[24:25], v[0:1]
	v_pk_mul_f32 v[0:1], v[200:201], v[202:203]
	v_pk_mul_f32 v[26:27], v[26:27], v[172:173]
	v_pk_mul_f32 v[172:173], v[212:213], v[214:215]
	v_pk_mul_f32 v[20:21], v[20:21], v[0:1]
	v_pk_mul_f32 v[22:23], v[22:23], v[172:173]
	s_waitcnt vmcnt(0)
; __device__ __forceinline__ float frcp(float x) { return __builtin_amdgcn_rcpf(x); }
;     static __device__ __forceinline__ void unpack8(u32x4 w, f32x4& a, f32x4& b) { a = (f32x4){::bflo(w.x), ::bfhi(w.x), ::bflo(w.y), ::bfhi(w.y)}; b = (f32x4){::bflo(w.z), ::bfhi(w.z), ::bflo(w.w), ::bfhi(w.w)}; }
;     __device__ __forceinline__ void mid(f32x4 (&acc)[2][2][4][2], const Unit& u, int seg, int wr, int wc, int fr, int fq) const {
;     ...
;         const bf16_t* const Gn = G + (seg - 1) * 1024;
; #pragma unroll
;         for (int ai = 0; ai < 2; ++ai)
; #pragma unroll
;             for (int m = 0; m < 4; ++m) {
;                 const size_t r = (size_t)(row0 + ai * HALF + m * 16);
;                 u32x4 gn[2], gd[2];
; #pragma unroll
;                 for (int bj = 0; bj < 2; ++bj) { gn[bj] = *(const u32x4*)(Gn + r * 3072 + col0 + bj * HALF); gd[bj] = *(const u32x4*)(Gn + r * 3072 + 1024 + col0 + bj * HALF); }
;                 f32x4 rt[2][2];
;                 __builtin_amdgcn_sched_barrier(0);
; #pragma unroll
;                 for (int bj = 0; bj < 2; ++bj) {
;                     f32x4 a0, a1, d0, d1; unpack8(gn[bj], a0, a1); unpack8(gd[bj], d0, d1);
; #pragma unroll
;                     for (int j = 0; j < 4; ++j) { rt[bj][0][j] = fmaxf(a0[j], 1e-30f) * ::frcp(fmaxf(d0[j], 1e-30f)); rt[bj][1][j] = fmaxf(a1[j], 1e-30f) * ::frcp(fmaxf(d1[j], 1e-30f)); }
;                 }
;                 __builtin_amdgcn_sched_barrier(0);
; #pragma unroll
;                 for (int bj = 0; bj < 2; ++bj) { acc[ai][bj][m][0] = acc[ai][bj][m][0] * rt[bj][0]; acc[ai][bj][m][1] = acc[ai][bj][m][1] * rt[bj][1]; }
;             }
	v_lshlrev_b32_e32 v3, 16, v217
	v_lshlrev_b32_e32 v204, 16, v221
	v_max_f32_e32 v3, v3, v3
	v_lshlrev_b32_e32 v172, 16, v220
	v_and_b32_e32 v173, 0xffff0000, v220
	v_max_f32_e32 v220, 0xda24260, v3
	v_max_f32_e32 v3, v204, v204
	v_lshlrev_b32_e32 v184, 16, v219
	v_max_f32_e32 v3, 0xda24260, v3
	v_and_b32_e32 v140, 0xffff0000, v217
	v_and_b32_e32 v185, 0xffff0000, v219
	v_and_b32_e32 v205, 0xffff0000, v221
	v_lshlrev_b32_e32 v217, 16, v222
	v_and_b32_e32 v219, 0xffff0000, v222
	v_lshlrev_b32_e32 v221, 16, v223
	v_rcp_f32_e32 v222, v3
	v_max_f32_e32 v3, v184, v184
	v_lshlrev_b32_e32 v141, 16, v218
	v_max_f32_e32 v204, 0xda24260, v3
	v_max_f32_e32 v3, v221, v221
	v_max_f32_e32 v141, v141, v141
	v_max_f32_e32 v3, 0xda24260, v3
	v_lshlrev_b32_e32 v0, 16, v216
	v_and_b32_e32 v1, 0xffff0000, v216
	v_max_f32_e32 v216, 0xda24260, v141
	v_max_f32_e32 v141, v217, v217
	v_rcp_f32_e32 v206, v3
	v_max_f32_e32 v3, v140, v140
	v_max_f32_e32 v141, 0xda24260, v141
	v_max_f32_e32 v221, 0xda24260, v3
	v_max_f32_e32 v3, v205, v205
	v_and_b32_e32 v145, 0xffff0000, v218
	v_rcp_f32_e32 v218, v141
	v_max_f32_e32 v141, v173, v173
	v_max_f32_e32 v3, 0xda24260, v3
	v_and_b32_e32 v207, 0xffff0000, v223
	v_max_f32_e32 v141, 0xda24260, v141
	v_rcp_f32_e32 v223, v3
	v_max_f32_e32 v3, v185, v185
	v_rcp_f32_e32 v173, v141
	v_max_f32_e32 v141, v145, v145
	v_max_f32_e32 v205, 0xda24260, v3
	v_max_f32_e32 v3, v207, v207
	v_max_f32_e32 v217, 0xda24260, v141
	v_max_f32_e32 v141, v219, v219
	v_max_f32_e32 v3, 0xda24260, v3
	v_max_f32_e32 v141, 0xda24260, v141
	v_rcp_f32_e32 v207, v3
	v_lshlrev_b32_e32 v3, 16, v224
	v_rcp_f32_e32 v219, v141
	v_lshlrev_b32_e32 v141, 16, v225
	v_and_b32_e32 v145, 0xffff0000, v225
	v_lshlrev_b32_e32 v225, 16, v228
	v_max_f32_e32 v3, v3, v3
	v_and_b32_e32 v140, 0xffff0000, v224
	v_max_f32_e32 v224, 0xda24260, v3
	v_max_f32_e32 v3, v225, v225
	v_lshlrev_b32_e32 v184, 16, v226
	v_max_f32_e32 v3, 0xda24260, v3
	v_and_b32_e32 v185, 0xffff0000, v226
	v_lshlrev_b32_e32 v210, 16, v229
	v_and_b32_e32 v211, 0xffff0000, v229
	v_lshlrev_b32_e32 v229, 16, v230
	v_rcp_f32_e32 v226, v3
	v_max_f32_e32 v3, v184, v184
	v_lshlrev_b32_e32 v209, 16, v227
	v_and_b32_e32 v213, 0xffff0000, v227
	v_and_b32_e32 v227, 0xffff0000, v228
	v_max_f32_e32 v228, 0xda24260, v3
	v_max_f32_e32 v3, v229, v229
	v_max_f32_e32 v3, 0xda24260, v3
	v_and_b32_e32 v208, 0xffff0000, v230
	v_rcp_f32_e32 v230, v3
	v_max_f32_e32 v3, v140, v140
	v_max_f32_e32 v225, 0xda24260, v3
	v_max_f32_e32 v3, v227, v227
	v_max_f32_e32 v3, 0xda24260, v3
	v_rcp_f32_e32 v227, v3
	v_max_f32_e32 v3, v185, v185
	v_max_f32_e32 v229, 0xda24260, v3
	v_max_f32_e32 v3, v208, v208
	v_max_f32_e32 v3, 0xda24260, v3
	v_lshlrev_b32_e32 v214, 16, v231
	v_and_b32_e32 v215, 0xffff0000, v231
	v_rcp_f32_e32 v231, v3
	v_max_f32_e32 v3, v141, v141
	v_max_f32_e32 v208, 0xda24260, v3
	v_max_f32_e32 v3, v210, v210
	v_max_f32_e32 v3, 0xda24260, v3
	v_rcp_f32_e32 v210, v3
	v_max_f32_e32 v3, v209, v209
	v_max_f32_e32 v212, 0xda24260, v3
	v_max_f32_e32 v3, v214, v214
	v_max_f32_e32 v140, v211, v211
	v_max_f32_e32 v3, 0xda24260, v3
	v_max_f32_e32 v140, 0xda24260, v140
	v_max_f32_e32 v172, v172, v172
	v_rcp_f32_e32 v214, v3
	v_max_f32_e32 v3, v145, v145
	v_rcp_f32_e32 v211, v140
	v_max_f32_e32 v140, v215, v215
	v_max_f32_e32 v0, v0, v0
	v_max_f32_e32 v172, 0xda24260, v172
	v_max_f32_e32 v1, v1, v1
	v_max_f32_e32 v140, 0xda24260, v140
	v_max_f32_e32 v209, 0xda24260, v3
	v_max_f32_e32 v3, v213, v213
	v_max_f32_e32 v0, 0xda24260, v0
	v_rcp_f32_e32 v172, v172
	v_max_f32_e32 v1, 0xda24260, v1
	v_rcp_f32_e32 v215, v140
	v_max_f32_e32 v213, 0xda24260, v3
	v_pk_mul_f32 v[0:1], v[0:1], v[172:173]
	v_pk_mul_f32 v[172:173], v[220:221], v[222:223]
	v_pk_mul_f32 v[16:17], v[16:17], v[0:1]
	v_pk_mul_f32 v[18:19], v[18:19], v[172:173]
	v_pk_mul_f32 v[0:1], v[216:217], v[218:219]
	v_pk_mul_f32 v[172:173], v[204:205], v[206:207]
	v_pk_mul_f32 v[12:13], v[12:13], v[0:1]
	v_pk_mul_f32 v[14:15], v[14:15], v[172:173]
	v_pk_mul_f32 v[0:1], v[224:225], v[226:227]
	v_pk_mul_f32 v[172:173], v[208:209], v[210:211]
	v_pk_mul_f32 v[8:9], v[8:9], v[0:1]
	v_pk_mul_f32 v[10:11], v[10:11], v[172:173]
	v_pk_mul_f32 v[0:1], v[228:229], v[230:231]
	v_pk_mul_f32 v[172:173], v[212:213], v[214:215]
	v_pk_mul_f32 v[4:5], v[4:5], v[0:1]
	v_pk_mul_f32 v[6:7], v[6:7], v[172:173]
	s_mov_b64 s[80:81], s[30:31]
	s_branch .LBB0_142
